# stack3 + write-through (sc1) stores in the P4 second epilogue loop only (less dirty L2 at the P4->P5 grid barrier)
# speedup vs baseline: 1.0123x; 1.0009x over previous
.LBB0_674:
	s_or_b64 exec, exec, s[6:7]
	s_add_i32 s3, s3, 5
	s_mul_hi_u32 s7, s3, 0x6000
	s_mulk_i32 s3, 0x6000
	v_readlane_b32 s8, v255, 14
	v_readlane_b32 s9, v255, 15
	s_add_u32 s6, s8, s3
	s_addc_u32 s7, s9, s7
	v_lshl_add_u64 v[164:165], s[6:7], 0, v[166:167]
	s_movk_i32 s3, 0x2000
	v_add_co_u32_e32 v170, vcc, s3, v164
	s_waitcnt lgkmcnt(0)
	s_barrier
	v_lshlrev_b32_e32 v130, 1, v162
	v_lshl_add_u64 v[168:169], s[66:67], 0, v[166:167]
	v_addc_co_u32_e32 v171, vcc, 0, v165, vcc
	v_and_b32_e32 v143, 48, v130
	s_waitcnt lgkmcnt(0)
	global_load_dwordx4 v[130:133], v[168:169], off offset:16
	global_load_dwordx4 v[134:137], v[168:169], off
	v_lshl_add_u64 v[166:167], v[164:165], 0, s[44:45]
	global_load_dwordx4 v[170:173], v[170:171], off
	s_nop 0
	global_load_dwordx4 v[178:181], v[166:167], off offset:16
	v_add_u32_e32 v184, s2, v160
	v_ashrrev_i32_e32 v185, 31, v184
	v_add_u32_e32 v139, 0x80, v162
	v_bfe_u32 v141, v162, 5, 1
	v_ashrrev_i32_e32 v145, 6, v162
	s_mov_b64 s[6:7], -1
	s_andn2_b64 vcc, exec, s[4:5]
	s_waitcnt vmcnt(1)
	v_pk_add_f32 v[172:173], v[172:173], 1.0 op_sel_hi:[1,0]
	v_pk_add_f32 v[170:171], v[170:171], 1.0 op_sel_hi:[1,0]
	v_pk_mul_f32 v[174:175], v[136:137], v[172:173]
	v_pk_mul_f32 v[176:177], v[134:135], v[170:171]
	s_waitcnt vmcnt(0)
	v_pk_add_f32 v[134:135], v[180:181], 1.0 op_sel_hi:[1,0]
	v_pk_add_f32 v[136:137], v[178:179], 1.0 op_sel_hi:[1,0]
	v_pk_mul_f32 v[170:171], v[132:133], v[134:135]
	v_pk_mul_f32 v[172:173], v[130:131], v[136:137]
	global_load_dwordx4 v[130:133], v[164:165], off offset:16
	global_load_dwordx4 v[134:137], v[164:165], off
	ds_read_b32 v186, v155
	v_lshlrev_b64 v[178:179], 12, v[184:185]
	v_cvt_pk_bf16_f32 v180, v122, v123
	v_cvt_pk_bf16_f32 v181, v124, v125
	v_cvt_pk_bf16_f32 v182, v126, v127
	v_lshl_add_u64 v[188:189], s[64:65], 0, v[178:179]
	v_lshlrev_b64 v[178:179], 1, v[162:163]
	s_waitcnt lgkmcnt(0)
	v_pk_mul_f32 v[124:125], v[124:125], v[186:187] op_sel_hi:[1,0]
	v_pk_mul_f32 v[122:123], v[122:123], v[186:187] op_sel_hi:[1,0]
	v_pk_mul_f32 v[126:127], v[126:127], v[186:187] op_sel_hi:[1,0]
	v_cvt_pk_bf16_f32 v183, v128, v129
	v_lshl_add_u64 v[162:163], v[188:189], 0, v[178:179]
	v_pk_mul_f32 v[128:129], v[128:129], v[186:187] op_sel_hi:[1,0]
	global_store_dwordx4 v[162:163], v[180:183], off sc1
	s_waitcnt vmcnt(2)
	v_pk_fma_f32 v[126:127], v[172:173], v[126:127], v[130:131]
	s_waitcnt vmcnt(1)
	v_pk_fma_f32 v[124:125], v[174:175], v[124:125], v[136:137]
	v_pk_fma_f32 v[122:123], v[176:177], v[122:123], v[134:135]
	v_pk_fma_f32 v[128:129], v[170:171], v[128:129], v[132:133]
	v_cvt_pk_bf16_f32 v122, v122, v123
	v_cvt_pk_bf16_f32 v123, v124, v125
	v_cvt_pk_bf16_f32 v124, v126, v127
	v_lshrrev_b32_e32 v127, 3, v160
	v_cvt_pk_bf16_f32 v125, v128, v129
	v_and_or_b32 v127, v127, 14, v141
	v_lshlrev_b32_e32 v128, 6, v184
	v_ashrrev_i32_e32 v126, 2, v184
	v_and_or_b32 v157, v128, s33, v143
	v_lshlrev_b32_e32 v128, 10, v127
	v_lshlrev_b32_e32 v127, 2, v184
	v_and_b32_e32 v126, 0xffffffe0, v126
	v_and_b32_e32 v127, 32, v127
	v_add_u32_e32 v129, v126, v145
	v_bitop3_b32 v127, v157, v128, v127 bitop3:0xde
	ds_read_b32 v160, v155 offset:64
	v_lshl_or_b32 v129, v129, 14, v127
	global_store_dwordx4 v129, v[122:125], s[62:63] sc1
	v_cvt_pk_bf16_f32 v180, v114, v115
	v_cvt_pk_bf16_f32 v181, v116, v117
	v_cvt_pk_bf16_f32 v182, v118, v119
	s_waitcnt lgkmcnt(0)
	v_pk_mul_f32 v[116:117], v[116:117], v[160:161] op_sel_hi:[1,0]
	v_pk_mul_f32 v[114:115], v[114:115], v[160:161] op_sel_hi:[1,0]
	v_add_u32_e32 v124, s2, v158
	v_ashrrev_i32_e32 v125, 31, v124
	v_lshlrev_b64 v[122:123], 12, v[124:125]
	v_lshl_add_u64 v[122:123], s[64:65], 0, v[122:123]
	v_pk_mul_f32 v[118:119], v[118:119], v[160:161] op_sel_hi:[1,0]
	v_cvt_pk_bf16_f32 v183, v120, v121
	v_lshl_add_u64 v[122:123], v[122:123], 0, v[178:179]
	v_pk_fma_f32 v[116:117], v[174:175], v[116:117], v[136:137]
	v_pk_fma_f32 v[114:115], v[176:177], v[114:115], v[134:135]
	v_pk_mul_f32 v[120:121], v[120:121], v[160:161] op_sel_hi:[1,0]
	v_pk_fma_f32 v[118:119], v[172:173], v[118:119], v[130:131]
	global_store_dwordx4 v[122:123], v[180:183], off sc1
	v_pk_fma_f32 v[120:121], v[170:171], v[120:121], v[132:133]
	v_cvt_pk_bf16_f32 v114, v114, v115
	v_cvt_pk_bf16_f32 v115, v116, v117
	v_cvt_pk_bf16_f32 v116, v118, v119
	v_lshrrev_b32_e32 v119, 3, v158
	v_cvt_pk_bf16_f32 v117, v120, v121
	v_ashrrev_i32_e32 v118, 2, v124
	v_and_or_b32 v119, v119, 14, v141
	v_lshlrev_b32_e32 v121, 6, v124
	v_lshlrev_b32_e32 v124, 2, v124
	v_and_b32_e32 v118, 0xffffffe0, v118
	v_and_or_b32 v121, v121, s33, v143
	v_lshlrev_b32_e32 v119, 10, v119
	v_and_b32_e32 v124, 32, v124
	v_add_u32_e32 v120, v118, v145
	v_bitop3_b32 v119, v121, v119, v124 bitop3:0xde
	v_lshl_or_b32 v120, v120, 14, v119
	global_store_dwordx4 v120, v[114:117], s[62:63] sc1
	ds_read_b32 v116, v155 offset:128
	v_add_u32_e32 v120, s2, v156
	v_ashrrev_i32_e32 v121, 31, v120
	v_lshlrev_b64 v[114:115], 12, v[120:121]
	v_cvt_pk_bf16_f32 v158, v34, v35
	v_lshl_add_u64 v[114:115], s[64:65], 0, v[114:115]
	s_waitcnt lgkmcnt(0)
	v_pk_mul_f32 v[34:35], v[34:35], v[116:117] op_sel_hi:[1,0]
	v_cvt_pk_bf16_f32 v159, v36, v37
	v_cvt_pk_bf16_f32 v160, v30, v31
	v_cvt_pk_bf16_f32 v161, v32, v33
	v_lshl_add_u64 v[114:115], v[114:115], 0, v[178:179]
	v_pk_mul_f32 v[36:37], v[36:37], v[116:117] op_sel_hi:[1,0]
	v_pk_fma_f32 v[34:35], v[176:177], v[34:35], v[134:135]
	v_pk_mul_f32 v[32:33], v[32:33], v[116:117] op_sel_hi:[1,0]
	v_pk_mul_f32 v[30:31], v[30:31], v[116:117] op_sel_hi:[1,0]
	global_store_dwordx4 v[114:115], v[158:161], off sc1
	v_pk_fma_f32 v[36:37], v[174:175], v[36:37], v[136:137]
	v_pk_fma_f32 v[116:117], v[170:171], v[32:33], v[132:133]
	v_pk_fma_f32 v[32:33], v[172:173], v[30:31], v[130:131]
	v_cvt_pk_bf16_f32 v30, v34, v35
	v_lshrrev_b32_e32 v35, 3, v156
	v_cvt_pk_bf16_f32 v31, v36, v37
	v_and_or_b32 v35, v35, 14, v141
	v_lshlrev_b32_e32 v36, 6, v120
	v_lshlrev_b32_e32 v37, 2, v120
	v_and_or_b32 v36, v36, s33, v143
	v_lshlrev_b32_e32 v35, 10, v35
	v_and_b32_e32 v37, 32, v37
	v_cvt_pk_bf16_f32 v32, v32, v33
	v_cvt_pk_bf16_f32 v33, v116, v117
	v_ashrrev_i32_e32 v34, 2, v120
	v_bitop3_b32 v117, v36, v35, v37 bitop3:0xde
	ds_read_b32 v36, v155 offset:192
	v_and_b32_e32 v116, 0xffffffe0, v34
	v_add_u32_e32 v34, v116, v145
	v_add_u32_e32 v124, s2, v154
	v_lshl_or_b32 v34, v34, 14, v117
	v_ashrrev_i32_e32 v125, 31, v124
	global_store_dwordx4 v34, v[30:33], s[62:63] sc1
	s_nop 1
	v_lshlrev_b64 v[30:31], 12, v[124:125]
	v_cvt_pk_bf16_f32 v32, v22, v23
	v_lshl_add_u64 v[30:31], s[64:65], 0, v[30:31]
	s_waitcnt lgkmcnt(0)
	v_pk_mul_f32 v[22:23], v[22:23], v[36:37] op_sel_hi:[1,0]
	v_cvt_pk_bf16_f32 v33, v24, v25
	v_cvt_pk_bf16_f32 v34, v18, v19
	v_cvt_pk_bf16_f32 v35, v20, v21
	v_lshl_add_u64 v[30:31], v[30:31], 0, v[178:179]
	v_pk_mul_f32 v[24:25], v[24:25], v[36:37] op_sel_hi:[1,0]
	v_pk_fma_f32 v[22:23], v[176:177], v[22:23], v[134:135]
	v_pk_mul_f32 v[20:21], v[20:21], v[36:37] op_sel_hi:[1,0]
	v_pk_mul_f32 v[18:19], v[18:19], v[36:37] op_sel_hi:[1,0]
	global_store_dwordx4 v[30:31], v[32:35], off sc1
	v_pk_fma_f32 v[24:25], v[174:175], v[24:25], v[136:137]
	s_nop 0
	v_pk_fma_f32 v[32:33], v[170:171], v[20:21], v[132:133]
	v_pk_fma_f32 v[20:21], v[172:173], v[18:19], v[130:131]
	v_cvt_pk_bf16_f32 v18, v22, v23
	v_lshrrev_b32_e32 v23, 3, v154
	v_cvt_pk_bf16_f32 v19, v24, v25
	v_ashrrev_i32_e32 v22, 2, v124
	v_and_or_b32 v23, v23, 14, v141
	v_lshlrev_b32_e32 v24, 6, v124
	v_lshlrev_b32_e32 v25, 2, v124
	v_and_b32_e32 v120, 0xffffffe0, v22
	v_and_or_b32 v24, v24, s33, v143
	v_lshlrev_b32_e32 v23, 10, v23
	v_and_b32_e32 v25, 32, v25
	v_add_u32_e32 v22, v120, v145
	v_bitop3_b32 v121, v24, v23, v25 bitop3:0xde
	v_lshl_or_b32 v22, v22, 14, v121
	v_cvt_pk_bf16_f32 v20, v20, v21
	v_cvt_pk_bf16_f32 v21, v32, v33
	global_store_dwordx4 v22, v[18:21], s[62:63] sc1
	v_add_u32_e32 v22, s2, v140
	ds_read_b32 v24, v155 offset:512
	v_ashrrev_i32_e32 v23, 31, v22
	v_lshlrev_b64 v[32:33], 12, v[22:23]
	v_lshl_add_u64 v[32:33], s[64:65], 0, v[32:33]
	v_cvt_pk_bf16_f32 v18, v42, v43
	v_cvt_pk_bf16_f32 v19, v44, v45
	v_cvt_pk_bf16_f32 v20, v38, v39
	v_cvt_pk_bf16_f32 v21, v40, v41
	v_lshl_add_u64 v[32:33], v[32:33], 0, v[178:179]
	global_store_dwordx4 v[32:33], v[18:21], off sc1
	v_ashrrev_i32_e32 v23, 2, v22
	v_and_b32_e32 v124, 0xffffffe0, v23
	s_waitcnt lgkmcnt(0)
	v_pk_mul_f32 v[18:19], v[44:45], v[24:25] op_sel_hi:[1,0]
	v_pk_mul_f32 v[20:21], v[42:43], v[24:25] op_sel_hi:[1,0]
	v_pk_fma_f32 v[34:35], v[174:175], v[18:19], v[136:137]
	v_pk_fma_f32 v[18:19], v[176:177], v[20:21], v[134:135]
	v_pk_mul_f32 v[20:21], v[40:41], v[24:25] op_sel_hi:[1,0]
	v_pk_mul_f32 v[24:25], v[38:39], v[24:25] op_sel_hi:[1,0]
	v_pk_fma_f32 v[36:37], v[170:171], v[20:21], v[132:133]
	v_pk_fma_f32 v[20:21], v[172:173], v[24:25], v[130:131]
	v_lshlrev_b32_e32 v24, 6, v22
	v_lshlrev_b32_e32 v22, 2, v22
	v_and_or_b32 v24, v24, s33, v143
	v_and_b32_e32 v22, 32, v22
	v_add_u32_e32 v23, v124, v145
	v_bitop3_b32 v125, v24, v128, v22 bitop3:0xde
	v_lshl_or_b32 v22, v23, 14, v125
	v_cvt_pk_bf16_f32 v18, v18, v19
	v_cvt_pk_bf16_f32 v19, v34, v35
	v_cvt_pk_bf16_f32 v20, v20, v21
	v_cvt_pk_bf16_f32 v21, v36, v37
	global_store_dwordx4 v22, v[18:21], s[62:63] sc1
	ds_read_b32 v22, v155 offset:576
	v_add_u32_e32 v24, s2, v138
	v_ashrrev_i32_e32 v25, 31, v24
	v_lshlrev_b64 v[34:35], 12, v[24:25]
	v_lshl_add_u64 v[34:35], s[64:65], 0, v[34:35]
	v_cvt_pk_bf16_f32 v18, v62, v63
	v_cvt_pk_bf16_f32 v19, v64, v65
	v_cvt_pk_bf16_f32 v20, v58, v59
	v_cvt_pk_bf16_f32 v21, v60, v61
	v_lshl_add_u64 v[34:35], v[34:35], 0, v[178:179]
	global_store_dwordx4 v[34:35], v[18:21], off sc1
	v_lshlrev_b32_e32 v25, 6, v24
	v_and_or_b32 v25, v25, s33, v143
	s_waitcnt lgkmcnt(0)
	v_pk_mul_f32 v[18:19], v[64:65], v[22:23] op_sel_hi:[1,0]
	v_pk_mul_f32 v[20:21], v[62:63], v[22:23] op_sel_hi:[1,0]
	v_pk_fma_f32 v[36:37], v[174:175], v[18:19], v[136:137]
	v_pk_fma_f32 v[18:19], v[176:177], v[20:21], v[134:135]
	v_pk_mul_f32 v[20:21], v[60:61], v[22:23] op_sel_hi:[1,0]
	v_pk_mul_f32 v[22:23], v[58:59], v[22:23] op_sel_hi:[1,0]
	v_pk_fma_f32 v[38:39], v[170:171], v[20:21], v[132:133]
	v_pk_fma_f32 v[20:21], v[172:173], v[22:23], v[130:131]
	v_lshrrev_b32_e32 v23, 3, v138
	v_ashrrev_i32_e32 v22, 2, v24
	v_and_or_b32 v23, v23, 14, v141
	v_lshlrev_b32_e32 v24, 2, v24
	v_and_b32_e32 v60, 0xffffffe0, v22
	v_lshlrev_b32_e32 v23, 10, v23
	v_and_b32_e32 v24, 32, v24
	v_add_u32_e32 v22, v60, v145
	v_bitop3_b32 v61, v25, v23, v24 bitop3:0xde
	v_lshl_or_b32 v22, v22, 14, v61
	v_cvt_pk_bf16_f32 v18, v18, v19
	v_cvt_pk_bf16_f32 v19, v36, v37
	v_cvt_pk_bf16_f32 v20, v20, v21
	v_cvt_pk_bf16_f32 v21, v38, v39
	global_store_dwordx4 v22, v[18:21], s[62:63] sc1
	v_add_u32_e32 v22, s2, v142
	ds_read_b32 v24, v155 offset:640
	v_ashrrev_i32_e32 v23, 31, v22
	v_lshlrev_b64 v[36:37], 12, v[22:23]
	v_lshl_add_u64 v[36:37], s[64:65], 0, v[36:37]
	v_cvt_pk_bf16_f32 v18, v70, v71
	v_cvt_pk_bf16_f32 v19, v72, v73
	v_cvt_pk_bf16_f32 v20, v66, v67
	v_cvt_pk_bf16_f32 v21, v68, v69
	v_lshl_add_u64 v[36:37], v[36:37], 0, v[178:179]
	global_store_dwordx4 v[36:37], v[18:21], off sc1
	v_ashrrev_i32_e32 v23, 2, v22
	v_and_b32_e32 v62, 0xffffffe0, v23
	s_waitcnt lgkmcnt(0)
	v_pk_mul_f32 v[18:19], v[72:73], v[24:25] op_sel_hi:[1,0]
	v_pk_mul_f32 v[20:21], v[70:71], v[24:25] op_sel_hi:[1,0]
	v_pk_fma_f32 v[38:39], v[174:175], v[18:19], v[136:137]
	v_pk_fma_f32 v[18:19], v[176:177], v[20:21], v[134:135]
	v_pk_mul_f32 v[20:21], v[68:69], v[24:25] op_sel_hi:[1,0]
	v_pk_mul_f32 v[24:25], v[66:67], v[24:25] op_sel_hi:[1,0]
	v_pk_fma_f32 v[40:41], v[170:171], v[20:21], v[132:133]
	v_pk_fma_f32 v[20:21], v[172:173], v[24:25], v[130:131]
	v_lshrrev_b32_e32 v24, 3, v142
	v_and_or_b32 v24, v24, 14, v141
	v_lshlrev_b32_e32 v25, 6, v22
	v_lshlrev_b32_e32 v22, 2, v22
	v_and_or_b32 v25, v25, s33, v143
	v_lshlrev_b32_e32 v24, 10, v24
	v_and_b32_e32 v22, 32, v22
	v_add_u32_e32 v23, v62, v145
	v_bitop3_b32 v63, v25, v24, v22 bitop3:0xde
	v_lshl_or_b32 v22, v23, 14, v63
	v_cvt_pk_bf16_f32 v18, v18, v19
	v_cvt_pk_bf16_f32 v19, v38, v39
	v_cvt_pk_bf16_f32 v20, v20, v21
	v_cvt_pk_bf16_f32 v21, v40, v41
	global_store_dwordx4 v22, v[18:21], s[62:63] sc1
	ds_read_b32 v22, v155 offset:704
	v_add_u32_e32 v24, s2, v144
	v_ashrrev_i32_e32 v25, 31, v24
	v_lshlrev_b64 v[38:39], 12, v[24:25]
	v_lshl_add_u64 v[38:39], s[64:65], 0, v[38:39]
	v_cvt_pk_bf16_f32 v18, v94, v95
	v_cvt_pk_bf16_f32 v19, v96, v97
	v_cvt_pk_bf16_f32 v20, v110, v111
	v_cvt_pk_bf16_f32 v21, v112, v113
	v_lshl_add_u64 v[38:39], v[38:39], 0, v[178:179]
	global_store_dwordx4 v[38:39], v[18:21], off sc1
	v_lshlrev_b32_e32 v25, 6, v24
	v_and_or_b32 v25, v25, s33, v143
	s_waitcnt lgkmcnt(0)
	v_pk_mul_f32 v[18:19], v[96:97], v[22:23] op_sel_hi:[1,0]
	v_pk_mul_f32 v[20:21], v[94:95], v[22:23] op_sel_hi:[1,0]
	v_pk_fma_f32 v[40:41], v[174:175], v[18:19], v[136:137]
	v_pk_fma_f32 v[18:19], v[176:177], v[20:21], v[134:135]
	v_pk_mul_f32 v[20:21], v[112:113], v[22:23] op_sel_hi:[1,0]
	v_pk_mul_f32 v[22:23], v[110:111], v[22:23] op_sel_hi:[1,0]
	v_pk_fma_f32 v[42:43], v[170:171], v[20:21], v[132:133]
	v_pk_fma_f32 v[20:21], v[172:173], v[22:23], v[130:131]
	v_lshrrev_b32_e32 v23, 3, v144
	v_ashrrev_i32_e32 v22, 2, v24
	v_and_or_b32 v23, v23, 14, v141
	v_lshlrev_b32_e32 v24, 2, v24
	v_and_b32_e32 v64, 0xffffffe0, v22
	v_lshlrev_b32_e32 v23, 10, v23
	v_and_b32_e32 v24, 32, v24
	v_add_u32_e32 v22, v64, v145
	v_bitop3_b32 v65, v25, v23, v24 bitop3:0xde
	v_lshl_or_b32 v22, v22, 14, v65
	v_cvt_pk_bf16_f32 v18, v18, v19
	v_cvt_pk_bf16_f32 v19, v40, v41
	v_cvt_pk_bf16_f32 v20, v20, v21
	v_cvt_pk_bf16_f32 v21, v42, v43
	global_store_dwordx4 v22, v[18:21], s[62:63] sc1
	global_load_dwordx4 v[18:21], v[168:169], off offset:528
	global_load_dwordx4 v[22:25], v[168:169], off offset:512
	global_load_dwordx4 v[40:43], v[166:167], off offset:528
	global_load_dwordx4 v[66:69], v[166:167], off offset:512
	v_ashrrev_i32_e32 v94, 6, v139
	s_waitcnt vmcnt(0)
	v_pk_add_f32 v[44:45], v[68:69], 1.0 op_sel_hi:[1,0]
	v_pk_add_f32 v[58:59], v[66:67], 1.0 op_sel_hi:[1,0]
	v_pk_mul_f32 v[44:45], v[24:25], v[44:45]
	v_pk_mul_f32 v[58:59], v[22:23], v[58:59]
	v_pk_add_f32 v[22:23], v[42:43], 1.0 op_sel_hi:[1,0]
	v_pk_add_f32 v[24:25], v[40:41], 1.0 op_sel_hi:[1,0]
	v_pk_mul_f32 v[40:41], v[20:21], v[22:23]
	v_pk_mul_f32 v[42:43], v[18:19], v[24:25]
	global_load_dwordx4 v[18:21], v[164:165], off offset:528
	global_load_dwordx4 v[22:25], v[164:165], off offset:512
	ds_read_b32 v70, v155
	v_cvt_pk_bf16_f32 v66, v86, v87
	v_cvt_pk_bf16_f32 v67, v88, v89
	v_cvt_pk_bf16_f32 v68, v82, v83
	v_cvt_pk_bf16_f32 v69, v84, v85
	global_store_dwordx4 v[162:163], v[66:69], off offset:256 sc1
	s_waitcnt lgkmcnt(0)
	s_nop 0
	v_pk_mul_f32 v[66:67], v[88:89], v[70:71] op_sel_hi:[1,0]
	v_pk_mul_f32 v[68:69], v[86:87], v[70:71] op_sel_hi:[1,0]
	s_waitcnt vmcnt(1)
	v_pk_fma_f32 v[72:73], v[44:45], v[66:67], v[24:25]
	v_pk_fma_f32 v[66:67], v[58:59], v[68:69], v[22:23]
	v_pk_mul_f32 v[68:69], v[84:85], v[70:71] op_sel_hi:[1,0]
	v_pk_mul_f32 v[70:71], v[82:83], v[70:71] op_sel_hi:[1,0]
	v_pk_fma_f32 v[82:83], v[40:41], v[68:69], v[20:21]
	v_pk_fma_f32 v[68:69], v[42:43], v[70:71], v[18:19]
	v_add_u32_e32 v70, v126, v94
	v_lshl_or_b32 v70, v70, 14, v127
	v_cvt_pk_bf16_f32 v66, v66, v67
	v_cvt_pk_bf16_f32 v67, v72, v73
	v_cvt_pk_bf16_f32 v68, v68, v69
	v_cvt_pk_bf16_f32 v69, v82, v83
	global_store_dwordx4 v70, v[66:69], s[62:63] sc1
	ds_read_b32 v70, v155 offset:64
	s_nop 0
	v_cvt_pk_bf16_f32 v66, v90, v91
	v_cvt_pk_bf16_f32 v67, v92, v93
	v_cvt_pk_bf16_f32 v68, v106, v107
	v_cvt_pk_bf16_f32 v69, v108, v109
	global_store_dwordx4 v[122:123], v[66:69], off offset:256 sc1
	s_waitcnt lgkmcnt(0)
	s_nop 0
	v_pk_mul_f32 v[66:67], v[92:93], v[70:71] op_sel_hi:[1,0]
	v_pk_mul_f32 v[68:69], v[90:91], v[70:71] op_sel_hi:[1,0]
	v_pk_fma_f32 v[72:73], v[44:45], v[66:67], v[24:25]
	v_pk_fma_f32 v[66:67], v[58:59], v[68:69], v[22:23]
	v_pk_mul_f32 v[68:69], v[108:109], v[70:71] op_sel_hi:[1,0]
	v_pk_mul_f32 v[70:71], v[106:107], v[70:71] op_sel_hi:[1,0]
	v_pk_fma_f32 v[82:83], v[40:41], v[68:69], v[20:21]
	v_pk_fma_f32 v[68:69], v[42:43], v[70:71], v[18:19]
	v_add_u32_e32 v70, v118, v94
	v_lshl_or_b32 v70, v70, 14, v119
	v_cvt_pk_bf16_f32 v66, v66, v67
	v_cvt_pk_bf16_f32 v67, v72, v73
	v_cvt_pk_bf16_f32 v68, v68, v69
	v_cvt_pk_bf16_f32 v69, v82, v83
	global_store_dwordx4 v70, v[66:69], s[62:63] sc1
	ds_read_b32 v70, v155 offset:128
	s_nop 0
	v_cvt_pk_bf16_f32 v66, v102, v103
	v_cvt_pk_bf16_f32 v67, v104, v105
	v_cvt_pk_bf16_f32 v68, v98, v99
	v_cvt_pk_bf16_f32 v69, v100, v101
	global_store_dwordx4 v[114:115], v[66:69], off offset:256 sc1
	s_waitcnt lgkmcnt(0)
	s_nop 0
	v_pk_mul_f32 v[66:67], v[104:105], v[70:71] op_sel_hi:[1,0]
	v_pk_mul_f32 v[68:69], v[102:103], v[70:71] op_sel_hi:[1,0]
	v_pk_fma_f32 v[72:73], v[44:45], v[66:67], v[24:25]
	v_pk_fma_f32 v[66:67], v[58:59], v[68:69], v[22:23]
	v_pk_mul_f32 v[68:69], v[100:101], v[70:71] op_sel_hi:[1,0]
	v_pk_mul_f32 v[70:71], v[98:99], v[70:71] op_sel_hi:[1,0]
	v_pk_fma_f32 v[82:83], v[40:41], v[68:69], v[20:21]
	v_pk_fma_f32 v[68:69], v[42:43], v[70:71], v[18:19]
	v_add_u32_e32 v70, v116, v94
	v_lshl_or_b32 v70, v70, 14, v117
	v_cvt_pk_bf16_f32 v66, v66, v67
	v_cvt_pk_bf16_f32 v67, v72, v73
	v_cvt_pk_bf16_f32 v68, v68, v69
	v_cvt_pk_bf16_f32 v69, v82, v83
	global_store_dwordx4 v70, v[66:69], s[62:63] sc1
	ds_read_b32 v70, v155 offset:192
	s_nop 0
	v_cvt_pk_bf16_f32 v66, v78, v79
	v_cvt_pk_bf16_f32 v67, v80, v81
	v_cvt_pk_bf16_f32 v68, v74, v75
	v_cvt_pk_bf16_f32 v69, v76, v77
	global_store_dwordx4 v[30:31], v[66:69], off offset:256 sc1
	s_waitcnt lgkmcnt(0)
	v_pk_mul_f32 v[30:31], v[80:81], v[70:71] op_sel_hi:[1,0]
	v_pk_mul_f32 v[66:67], v[78:79], v[70:71] op_sel_hi:[1,0]
	v_pk_fma_f32 v[30:31], v[44:45], v[30:31], v[24:25]
	v_pk_fma_f32 v[66:67], v[58:59], v[66:67], v[22:23]
	v_pk_mul_f32 v[68:69], v[76:77], v[70:71] op_sel_hi:[1,0]
	v_pk_mul_f32 v[70:71], v[74:75], v[70:71] op_sel_hi:[1,0]
	v_cvt_pk_bf16_f32 v66, v66, v67
	v_cvt_pk_bf16_f32 v67, v30, v31
	v_add_u32_e32 v30, v120, v94
	v_pk_fma_f32 v[72:73], v[40:41], v[68:69], v[20:21]
	v_pk_fma_f32 v[68:69], v[42:43], v[70:71], v[18:19]
	v_lshl_or_b32 v30, v30, 14, v121
	v_cvt_pk_bf16_f32 v68, v68, v69
	v_cvt_pk_bf16_f32 v69, v72, v73
	global_store_dwordx4 v30, v[66:69], s[62:63] sc1
	ds_read_b32 v30, v155 offset:512
	s_nop 0
	v_cvt_pk_bf16_f32 v66, v54, v55
	v_cvt_pk_bf16_f32 v67, v56, v57
	v_cvt_pk_bf16_f32 v68, v50, v51
	v_cvt_pk_bf16_f32 v69, v52, v53
	global_store_dwordx4 v[32:33], v[66:69], off offset:256 sc1
	s_waitcnt lgkmcnt(0)
	v_pk_mul_f32 v[32:33], v[56:57], v[30:31] op_sel_hi:[1,0]
	v_pk_mul_f32 v[52:53], v[52:53], v[30:31] op_sel_hi:[1,0]
	v_pk_mul_f32 v[54:55], v[54:55], v[30:31] op_sel_hi:[1,0]
	v_pk_fma_f32 v[32:33], v[44:45], v[32:33], v[24:25]
	v_pk_mul_f32 v[30:31], v[50:51], v[30:31] op_sel_hi:[1,0]
	v_pk_fma_f32 v[50:51], v[40:41], v[52:53], v[20:21]
	v_pk_fma_f32 v[54:55], v[58:59], v[54:55], v[22:23]
	v_pk_fma_f32 v[52:53], v[42:43], v[30:31], v[18:19]
	v_cvt_pk_bf16_f32 v30, v54, v55
	v_cvt_pk_bf16_f32 v31, v32, v33
	s_nop 0
	v_cvt_pk_bf16_f32 v32, v52, v53
	v_cvt_pk_bf16_f32 v33, v50, v51
	v_add_u32_e32 v50, v124, v94
	v_lshl_or_b32 v50, v50, 14, v125
	global_store_dwordx4 v50, v[30:33], s[62:63] sc1
	ds_read_b32 v50, v155 offset:576
	s_nop 0
	v_cvt_pk_bf16_f32 v30, v46, v47
	v_cvt_pk_bf16_f32 v31, v48, v49
	v_cvt_pk_bf16_f32 v32, v26, v27
	v_cvt_pk_bf16_f32 v33, v28, v29
	global_store_dwordx4 v[34:35], v[30:33], off offset:256 sc1
	s_waitcnt lgkmcnt(0)
	v_pk_mul_f32 v[28:29], v[28:29], v[50:51] op_sel_hi:[1,0]
	v_pk_mul_f32 v[26:27], v[26:27], v[50:51] op_sel_hi:[1,0]
	v_pk_mul_f32 v[30:31], v[48:49], v[50:51] op_sel_hi:[1,0]
	v_pk_mul_f32 v[32:33], v[46:47], v[50:51] op_sel_hi:[1,0]
	v_pk_fma_f32 v[30:31], v[44:45], v[30:31], v[24:25]
	v_pk_fma_f32 v[32:33], v[58:59], v[32:33], v[22:23]
	v_pk_fma_f32 v[34:35], v[40:41], v[28:29], v[20:21]
	v_pk_fma_f32 v[28:29], v[42:43], v[26:27], v[18:19]
	v_cvt_pk_bf16_f32 v26, v32, v33
	v_cvt_pk_bf16_f32 v27, v30, v31
	v_add_u32_e32 v30, v60, v94
	v_lshl_or_b32 v30, v30, 14, v61
	v_cvt_pk_bf16_f32 v28, v28, v29
	v_cvt_pk_bf16_f32 v29, v34, v35
	global_store_dwordx4 v30, v[26:29], s[62:63] sc1
	ds_read_b32 v30, v155 offset:640
	s_nop 0
	v_cvt_pk_bf16_f32 v26, v14, v15
	v_cvt_pk_bf16_f32 v27, v16, v17
	v_cvt_pk_bf16_f32 v28, v10, v11
	s_waitcnt lgkmcnt(0)
	v_pk_mul_f32 v[14:15], v[14:15], v[30:31] op_sel_hi:[1,0]
	v_cvt_pk_bf16_f32 v29, v12, v13
	v_pk_mul_f32 v[12:13], v[12:13], v[30:31] op_sel_hi:[1,0]
	v_pk_fma_f32 v[14:15], v[58:59], v[14:15], v[22:23]
	v_pk_mul_f32 v[10:11], v[10:11], v[30:31] op_sel_hi:[1,0]
	global_store_dwordx4 v[36:37], v[26:29], off offset:256 sc1
	v_pk_mul_f32 v[16:17], v[16:17], v[30:31] op_sel_hi:[1,0]
	s_nop 0
	v_pk_fma_f32 v[26:27], v[40:41], v[12:13], v[20:21]
	v_pk_fma_f32 v[12:13], v[42:43], v[10:11], v[18:19]
	v_cvt_pk_bf16_f32 v10, v14, v15
	v_add_u32_e32 v14, v62, v94
	v_lshl_or_b32 v14, v14, 14, v63
	v_pk_fma_f32 v[16:17], v[44:45], v[16:17], v[24:25]
	s_nop 0
	v_cvt_pk_bf16_f32 v11, v16, v17
	v_cvt_pk_bf16_f32 v12, v12, v13
	v_cvt_pk_bf16_f32 v13, v26, v27
	global_store_dwordx4 v14, v[10:13], s[62:63] sc1
	ds_read_b32 v14, v155 offset:704
	s_nop 0
	v_cvt_pk_bf16_f32 v10, v6, v7
	v_cvt_pk_bf16_f32 v11, v8, v9
	v_cvt_pk_bf16_f32 v12, v2, v3
	s_waitcnt lgkmcnt(0)
	v_pk_mul_f32 v[6:7], v[6:7], v[14:15] op_sel_hi:[1,0]
	v_cvt_pk_bf16_f32 v13, v4, v5
	v_pk_mul_f32 v[4:5], v[4:5], v[14:15] op_sel_hi:[1,0]
	v_pk_fma_f32 v[6:7], v[58:59], v[6:7], v[22:23]
	v_pk_mul_f32 v[2:3], v[2:3], v[14:15] op_sel_hi:[1,0]
	global_store_dwordx4 v[38:39], v[10:13], off offset:256 sc1
	v_pk_mul_f32 v[8:9], v[8:9], v[14:15] op_sel_hi:[1,0]
	s_nop 0
	v_pk_fma_f32 v[10:11], v[40:41], v[4:5], v[20:21]
	v_pk_fma_f32 v[4:5], v[42:43], v[2:3], v[18:19]
	v_cvt_pk_bf16_f32 v2, v6, v7
	v_add_u32_e32 v6, v64, v94
	v_lshl_or_b32 v6, v6, 14, v65
	v_pk_fma_f32 v[8:9], v[44:45], v[8:9], v[24:25]
	s_nop 0
	v_cvt_pk_bf16_f32 v3, v8, v9
	v_cvt_pk_bf16_f32 v4, v4, v5
	v_cvt_pk_bf16_f32 v5, v10, v11
	global_store_dwordx4 v6, v[2:5], s[62:63] sc1
	s_cbranch_vccnz .LBB0_587
	s_andn2_b64 vcc, exec, s[46:47]
	s_cbranch_vccnz .LBB0_586
	s_barrier
	s_branch .LBB0_586
